# v26: v25 + prologue conditioning-vector loop: its 16 per-thread loads touched up front so the serialized loop loads hit cache (prologue de-serialisation)
# baseline (speedup 1.0000x reference)
; #define LAS __attribute__((address_space(3)))
; __device__ __forceinline__ void prologue(const Params& p, LAS unsigned char* lds, int tid, int wave, int lane, int G) {
;     ...
;     __syncthreads();
;     {
;         LAS float* cond = (LAS float*)lds;
;         LAS float* red = (LAS float*)(lds + 32768);
;         for (int i = tid; i < NBATCH * DM; i += NTHREADS) { const float cv = p.c[i]; cond[i] = cv / (1.0f + __expf(-cv)); }
.LBB0_805:
	s_movk_i32 s0, 0x2000
	v_cmp_gt_i32_e32 vcc, s0, v38
	s_waitcnt lgkmcnt(0)
	v_lshlrev_b32_e32 v2, 2, v38
	v_ashrrev_i32_e32 v39, 31, v38
	s_barrier
	s_and_saveexec_b64 s[0:1], vcc
	s_mov_b64 s[16:17], 0x800
	s_cbranch_execz .LBB0_808
	v_add_u32_e32 v3, 0xfffffe00, v38
	v_add_u32_e32 v4, 0, v2
	v_lshl_add_u64 v[0:1], v[38:39], 2, s[82:83]
	s_mov_b64 vcc, 0x1000
	v_mov_b64_e32 v[100:101], v[0:1]
	global_load_dword v104, v[100:101], off
	global_load_dword v104, v[100:101], off offset:2048
	v_lshl_add_u64 v[100:101], v[100:101], 0, vcc
	global_load_dword v104, v[100:101], off
	global_load_dword v104, v[100:101], off offset:2048
	v_lshl_add_u64 v[100:101], v[100:101], 0, vcc
	global_load_dword v104, v[100:101], off
	global_load_dword v104, v[100:101], off offset:2048
	v_lshl_add_u64 v[100:101], v[100:101], 0, vcc
	global_load_dword v104, v[100:101], off
	global_load_dword v104, v[100:101], off offset:2048
	v_lshl_add_u64 v[100:101], v[100:101], 0, vcc
	global_load_dword v104, v[100:101], off
	global_load_dword v104, v[100:101], off offset:2048
	v_lshl_add_u64 v[100:101], v[100:101], 0, vcc
	global_load_dword v104, v[100:101], off
	global_load_dword v104, v[100:101], off offset:2048
	v_lshl_add_u64 v[100:101], v[100:101], 0, vcc
	global_load_dword v104, v[100:101], off
	global_load_dword v104, v[100:101], off offset:2048
	v_lshl_add_u64 v[100:101], v[100:101], 0, vcc
	global_load_dword v104, v[100:101], off
	global_load_dword v104, v[100:101], off offset:2048
	s_mov_b64 s[12:13], 0
